# P2 q up-projection epilogue: 16 ssq loads batched up front, counted vmcnt (on top of v19)
# baseline (speedup 1.0000x reference)
; __device__ __forceinline__ u32x4 pk8(const f32x4& a, const f32x4& b) { u32x4 w; w.x = pk(a[0], a[1]); w.y = pk(a[2], a[3]); w.z = pk(b[0], b[1]); w.w = pk(b[2], b[3]); return w; }
;     __device__ __forceinline__ void operator()(const f32x4 (&acc)[2][2][4][2], const pg8::Unit& u, int wr, int wc, int fr, int fq) const { if (u.job) kv(acc, u, wr, wc, fr, fq); else q(acc, u, wr, wc, fr, fq); }
;     __device__ __forceinline__ void operator()(const f32x4 (&acc)[2][2][4][2], const pg8::Unit& u, int wr, int wc, int fr, int fq) const { if (u.job) e1(acc, u, wr, wc, fr, fq); else e0(acc, u, wr, wc, fr, fq); }
;     __device__ __forceinline__ void operator()(const f32x4 (&acc)[2][2][4][2], const pg8::Unit& u, int wr, int wc, int fr, int fq) const {
;         const int row0 = u.pm * 256 + wr * 64 + fr; bf16_t* dst = O + u.pn * 256 + wc * 32 + 8 * fq;
; #pragma unroll
;         for (int ai = 0; ai < 2; ++ai)
; #pragma unroll
;             for (int m = 0; m < 4; ++m) {
;                 const int row = row0 + ai * 128 + m * 16; float rs = 1.f;
;                 if (ssq) { const f32x4 a = *(const f32x4*)(ssq + (size_t)row * 8), b = *(const f32x4*)(ssq + (size_t)row * 8 + 4);
;                     rs = __builtin_amdgcn_rsqf((((a[0] + a[1]) + (a[2] + a[3])) + ((b[0] + b[1]) + (b[2] + b[3]))) * inv_k + EPS); }
; #pragma unroll
;                 for (int bj = 0; bj < 2; ++bj) *(u32x4*)(dst + (size_t)row * ldc + bj * 128) = pk8(acc[ai][bj][m][0] * rs, acc[ai][bj][m][1] * rs);
;             }
.LBB0_919:
	v_readlane_b32 s34, v252, 60
	v_readlane_b32 s35, v252, 61
	s_lshl_b32 s2, s36, 8
	s_ashr_i32 s3, s2, 31
	v_lshlrev_b32_e32 v224, 5, v222
	v_add_u32_e32 v225, 0x1000, v224
	v_lshl_add_u64 v[228:229], s[2:3], 1, v[212:213]
	v_mad_i64_i32 v[226:227], s[2:3], v222, s29, v[228:229]
	s_mov_b64 s[98:99], 0x18000
	s_mov_b64 s[100:101], 0x78000
	global_load_dwordx4 v[128:131], v224, s[34:35]
	global_load_dwordx4 v[132:135], v224, s[34:35] offset:16
	global_load_dwordx4 v[136:139], v224, s[34:35] offset:512
	global_load_dwordx4 v[140:143], v224, s[34:35] offset:528
	global_load_dwordx4 v[144:147], v224, s[34:35] offset:1024
	global_load_dwordx4 v[148:151], v224, s[34:35] offset:1040
	global_load_dwordx4 v[152:155], v224, s[34:35] offset:1536
	global_load_dwordx4 v[156:159], v224, s[34:35] offset:1552
	global_load_dwordx4 v[160:163], v225, s[34:35]
	global_load_dwordx4 v[164:167], v225, s[34:35] offset:16
	global_load_dwordx4 v[168:171], v225, s[34:35] offset:512
	global_load_dwordx4 v[172:175], v225, s[34:35] offset:528
	global_load_dwordx4 v[176:179], v225, s[34:35] offset:1024
	global_load_dwordx4 v[180:183], v225, s[34:35] offset:1040
	global_load_dwordx4 v[188:191], v225, s[34:35] offset:1536
	global_load_dwordx4 v[194:197], v225, s[34:35] offset:1552
	s_waitcnt vmcnt(14)
	v_add_f32_e32 v230, v128, v129
	v_add_f32_e32 v231, v130, v131
	v_add_f32_e32 v232, v132, v133
	v_add_f32_e32 v233, v134, v135
	v_add_f32_e32 v230, v230, v231
	v_add_f32_e32 v232, v232, v233
	v_add_f32_e32 v230, v230, v232
	v_fmamk_f32 v230, v230, 0x3b000000, v241
	v_rsq_f32_e32 v230, v230
	s_nop 0
	v_mul_f32_e32 v124, v124, v230
	v_mul_f32_e32 v125, v125, v230
	v_mul_f32_e32 v126, v126, v230
	v_mul_f32_e32 v127, v127, v230
	v_mul_f32_e32 v120, v120, v230
	v_mul_f32_e32 v121, v121, v230
	v_mul_f32_e32 v122, v122, v230
	v_mul_f32_e32 v123, v123, v230
	v_cvt_pk_bf16_f32 v128, v124, v125
	v_cvt_pk_bf16_f32 v129, v126, v127
	v_cvt_pk_bf16_f32 v130, v120, v121
	v_cvt_pk_bf16_f32 v131, v122, v123
	global_store_dwordx4 v[226:227], v[128:131], off
	v_mul_f32_e32 v116, v116, v230
	v_mul_f32_e32 v117, v117, v230
	v_mul_f32_e32 v118, v118, v230
	v_mul_f32_e32 v119, v119, v230
	v_mul_f32_e32 v112, v112, v230
	v_mul_f32_e32 v113, v113, v230
	v_mul_f32_e32 v114, v114, v230
	v_mul_f32_e32 v115, v115, v230
	v_cvt_pk_bf16_f32 v132, v116, v117
	v_cvt_pk_bf16_f32 v133, v118, v119
	v_cvt_pk_bf16_f32 v134, v112, v113
	v_cvt_pk_bf16_f32 v135, v114, v115
	global_store_dwordx4 v[226:227], v[132:135], off offset:256
	v_lshl_add_u64 v[226:227], v[226:227], 0, s[98:99]
	s_waitcnt vmcnt(14)
	v_add_f32_e32 v230, v136, v137
	v_add_f32_e32 v231, v138, v139
	v_add_f32_e32 v232, v140, v141
	v_add_f32_e32 v233, v142, v143
	v_add_f32_e32 v230, v230, v231
	v_add_f32_e32 v232, v232, v233
	v_add_f32_e32 v230, v230, v232
	v_fmamk_f32 v230, v230, 0x3b000000, v241
	v_rsq_f32_e32 v230, v230
	s_nop 0
	v_mul_f32_e32 v108, v108, v230
	v_mul_f32_e32 v109, v109, v230
	v_mul_f32_e32 v110, v110, v230
	v_mul_f32_e32 v111, v111, v230
	v_mul_f32_e32 v104, v104, v230
	v_mul_f32_e32 v105, v105, v230
	v_mul_f32_e32 v106, v106, v230
	v_mul_f32_e32 v107, v107, v230
	v_cvt_pk_bf16_f32 v136, v108, v109
	v_cvt_pk_bf16_f32 v137, v110, v111
	v_cvt_pk_bf16_f32 v138, v104, v105
	v_cvt_pk_bf16_f32 v139, v106, v107
	global_store_dwordx4 v[226:227], v[136:139], off
	v_mul_f32_e32 v100, v100, v230
	v_mul_f32_e32 v101, v101, v230
	v_mul_f32_e32 v102, v102, v230
	v_mul_f32_e32 v103, v103, v230
	v_mul_f32_e32 v96, v96, v230
	v_mul_f32_e32 v97, v97, v230
	v_mul_f32_e32 v98, v98, v230
	v_mul_f32_e32 v99, v99, v230
	v_cvt_pk_bf16_f32 v140, v100, v101
	v_cvt_pk_bf16_f32 v141, v102, v103
	v_cvt_pk_bf16_f32 v142, v96, v97
	v_cvt_pk_bf16_f32 v143, v98, v99
	global_store_dwordx4 v[226:227], v[140:143], off offset:256
	v_lshl_add_u64 v[226:227], v[226:227], 0, s[98:99]
	s_waitcnt vmcnt(14)
	v_add_f32_e32 v230, v144, v145
	v_add_f32_e32 v231, v146, v147
	v_add_f32_e32 v232, v148, v149
	v_add_f32_e32 v233, v150, v151
	v_add_f32_e32 v230, v230, v231
	v_add_f32_e32 v232, v232, v233
	v_add_f32_e32 v230, v230, v232
	v_fmamk_f32 v230, v230, 0x3b000000, v241
	v_rsq_f32_e32 v230, v230
	s_nop 0
	v_mul_f32_e32 v92, v92, v230
	v_mul_f32_e32 v93, v93, v230
	v_mul_f32_e32 v94, v94, v230
	v_mul_f32_e32 v95, v95, v230
	v_mul_f32_e32 v88, v88, v230
	v_mul_f32_e32 v89, v89, v230
	v_mul_f32_e32 v90, v90, v230
	v_mul_f32_e32 v91, v91, v230
	v_cvt_pk_bf16_f32 v144, v92, v93
	v_cvt_pk_bf16_f32 v145, v94, v95
	v_cvt_pk_bf16_f32 v146, v88, v89
	v_cvt_pk_bf16_f32 v147, v90, v91
	global_store_dwordx4 v[226:227], v[144:147], off
	v_mul_f32_e32 v84, v84, v230
	v_mul_f32_e32 v85, v85, v230
	v_mul_f32_e32 v86, v86, v230
	v_mul_f32_e32 v87, v87, v230
	v_mul_f32_e32 v80, v80, v230
	v_mul_f32_e32 v81, v81, v230
	v_mul_f32_e32 v82, v82, v230
	v_mul_f32_e32 v83, v83, v230
	v_cvt_pk_bf16_f32 v148, v84, v85
	v_cvt_pk_bf16_f32 v149, v86, v87
	v_cvt_pk_bf16_f32 v150, v80, v81
	v_cvt_pk_bf16_f32 v151, v82, v83
	global_store_dwordx4 v[226:227], v[148:151], off offset:256
	v_lshl_add_u64 v[226:227], v[226:227], 0, s[98:99]
	s_waitcnt vmcnt(14)
; __device__ __forceinline__ u32x4 pk8(const f32x4& a, const f32x4& b) { u32x4 w; w.x = pk(a[0], a[1]); w.y = pk(a[2], a[3]); w.z = pk(b[0], b[1]); w.w = pk(b[2], b[3]); return w; }
;     __device__ __forceinline__ void operator()(const f32x4 (&acc)[2][2][4][2], const pg8::Unit& u, int wr, int wc, int fr, int fq) const { if (u.job) kv(acc, u, wr, wc, fr, fq); else q(acc, u, wr, wc, fr, fq); }
;     __device__ __forceinline__ void operator()(const f32x4 (&acc)[2][2][4][2], const pg8::Unit& u, int wr, int wc, int fr, int fq) const { if (u.job) e1(acc, u, wr, wc, fr, fq); else e0(acc, u, wr, wc, fr, fq); }
;     __device__ __forceinline__ void operator()(const f32x4 (&acc)[2][2][4][2], const pg8::Unit& u, int wr, int wc, int fr, int fq) const {
;         const int row0 = u.pm * 256 + wr * 64 + fr; bf16_t* dst = O + u.pn * 256 + wc * 32 + 8 * fq;
; #pragma unroll
;         for (int ai = 0; ai < 2; ++ai)
; #pragma unroll
;             for (int m = 0; m < 4; ++m) {
;                 const int row = row0 + ai * 128 + m * 16; float rs = 1.f;
;                 if (ssq) { const f32x4 a = *(const f32x4*)(ssq + (size_t)row * 8), b = *(const f32x4*)(ssq + (size_t)row * 8 + 4);
;                     rs = __builtin_amdgcn_rsqf((((a[0] + a[1]) + (a[2] + a[3])) + ((b[0] + b[1]) + (b[2] + b[3]))) * inv_k + EPS); }
; #pragma unroll
;                 for (int bj = 0; bj < 2; ++bj) *(u32x4*)(dst + (size_t)row * ldc + bj * 128) = pk8(acc[ai][bj][m][0] * rs, acc[ai][bj][m][1] * rs);
;             }
	v_add_f32_e32 v230, v152, v153
	v_add_f32_e32 v231, v154, v155
	v_add_f32_e32 v232, v156, v157
	v_add_f32_e32 v233, v158, v159
	v_add_f32_e32 v230, v230, v231
	v_add_f32_e32 v232, v232, v233
	v_add_f32_e32 v230, v230, v232
	v_fmamk_f32 v230, v230, 0x3b000000, v241
	v_rsq_f32_e32 v230, v230
	s_nop 0
	v_mul_f32_e32 v76, v76, v230
	v_mul_f32_e32 v77, v77, v230
	v_mul_f32_e32 v78, v78, v230
	v_mul_f32_e32 v79, v79, v230
	v_mul_f32_e32 v72, v72, v230
	v_mul_f32_e32 v73, v73, v230
	v_mul_f32_e32 v74, v74, v230
	v_mul_f32_e32 v75, v75, v230
	v_cvt_pk_bf16_f32 v152, v76, v77
	v_cvt_pk_bf16_f32 v153, v78, v79
	v_cvt_pk_bf16_f32 v154, v72, v73
	v_cvt_pk_bf16_f32 v155, v74, v75
	global_store_dwordx4 v[226:227], v[152:155], off
	v_mul_f32_e32 v68, v68, v230
	v_mul_f32_e32 v69, v69, v230
	v_mul_f32_e32 v70, v70, v230
	v_mul_f32_e32 v71, v71, v230
	v_mul_f32_e32 v64, v64, v230
	v_mul_f32_e32 v65, v65, v230
	v_mul_f32_e32 v66, v66, v230
	v_mul_f32_e32 v67, v67, v230
	v_cvt_pk_bf16_f32 v156, v68, v69
	v_cvt_pk_bf16_f32 v157, v70, v71
	v_cvt_pk_bf16_f32 v158, v64, v65
	v_cvt_pk_bf16_f32 v159, v66, v67
	global_store_dwordx4 v[226:227], v[156:159], off offset:256
	v_lshl_add_u64 v[226:227], v[226:227], 0, s[100:101]
	s_waitcnt vmcnt(14)
	v_add_f32_e32 v230, v160, v161
	v_add_f32_e32 v231, v162, v163
	v_add_f32_e32 v232, v164, v165
	v_add_f32_e32 v233, v166, v167
	v_add_f32_e32 v230, v230, v231
	v_add_f32_e32 v232, v232, v233
	v_add_f32_e32 v230, v230, v232
	v_fmamk_f32 v230, v230, 0x3b000000, v241
	v_rsq_f32_e32 v230, v230
	s_nop 0
	v_mul_f32_e32 v60, v60, v230
	v_mul_f32_e32 v61, v61, v230
	v_mul_f32_e32 v62, v62, v230
	v_mul_f32_e32 v63, v63, v230
	v_mul_f32_e32 v56, v56, v230
	v_mul_f32_e32 v57, v57, v230
	v_mul_f32_e32 v58, v58, v230
	v_mul_f32_e32 v59, v59, v230
	v_cvt_pk_bf16_f32 v160, v60, v61
	v_cvt_pk_bf16_f32 v161, v62, v63
	v_cvt_pk_bf16_f32 v162, v56, v57
	v_cvt_pk_bf16_f32 v163, v58, v59
	global_store_dwordx4 v[226:227], v[160:163], off
	v_mul_f32_e32 v52, v52, v230
	v_mul_f32_e32 v53, v53, v230
	v_mul_f32_e32 v54, v54, v230
	v_mul_f32_e32 v55, v55, v230
	v_mul_f32_e32 v48, v48, v230
	v_mul_f32_e32 v49, v49, v230
	v_mul_f32_e32 v50, v50, v230
	v_mul_f32_e32 v51, v51, v230
	v_cvt_pk_bf16_f32 v164, v52, v53
	v_cvt_pk_bf16_f32 v165, v54, v55
	v_cvt_pk_bf16_f32 v166, v48, v49
	v_cvt_pk_bf16_f32 v167, v50, v51
	global_store_dwordx4 v[226:227], v[164:167], off offset:256
	v_lshl_add_u64 v[226:227], v[226:227], 0, s[98:99]
	s_waitcnt vmcnt(14)
	v_add_f32_e32 v230, v168, v169
	v_add_f32_e32 v231, v170, v171
	v_add_f32_e32 v232, v172, v173
	v_add_f32_e32 v233, v174, v175
	v_add_f32_e32 v230, v230, v231
	v_add_f32_e32 v232, v232, v233
	v_add_f32_e32 v230, v230, v232
	v_fmamk_f32 v230, v230, 0x3b000000, v241
	v_rsq_f32_e32 v230, v230
	s_nop 0
	v_mul_f32_e32 v44, v44, v230
	v_mul_f32_e32 v45, v45, v230
	v_mul_f32_e32 v46, v46, v230
	v_mul_f32_e32 v47, v47, v230
	v_mul_f32_e32 v40, v40, v230
	v_mul_f32_e32 v41, v41, v230
	v_mul_f32_e32 v42, v42, v230
	v_mul_f32_e32 v43, v43, v230
	v_cvt_pk_bf16_f32 v168, v44, v45
	v_cvt_pk_bf16_f32 v169, v46, v47
	v_cvt_pk_bf16_f32 v170, v40, v41
	v_cvt_pk_bf16_f32 v171, v42, v43
	global_store_dwordx4 v[226:227], v[168:171], off
	v_mul_f32_e32 v36, v36, v230
	v_mul_f32_e32 v37, v37, v230
	v_mul_f32_e32 v38, v38, v230
	v_mul_f32_e32 v39, v39, v230
	v_mul_f32_e32 v32, v32, v230
	v_mul_f32_e32 v33, v33, v230
	v_mul_f32_e32 v34, v34, v230
	v_mul_f32_e32 v35, v35, v230
	v_cvt_pk_bf16_f32 v172, v36, v37
	v_cvt_pk_bf16_f32 v173, v38, v39
	v_cvt_pk_bf16_f32 v174, v32, v33
	v_cvt_pk_bf16_f32 v175, v34, v35
	global_store_dwordx4 v[226:227], v[172:175], off offset:256
	v_lshl_add_u64 v[226:227], v[226:227], 0, s[98:99]
	s_waitcnt vmcnt(14)
	v_add_f32_e32 v230, v176, v177
	v_add_f32_e32 v231, v178, v179
	v_add_f32_e32 v232, v180, v181
	v_add_f32_e32 v233, v182, v183
	v_add_f32_e32 v230, v230, v231
	v_add_f32_e32 v232, v232, v233
	v_add_f32_e32 v230, v230, v232
	v_fmamk_f32 v230, v230, 0x3b000000, v241
	v_rsq_f32_e32 v230, v230
	s_nop 0
	v_mul_f32_e32 v28, v28, v230
	v_mul_f32_e32 v29, v29, v230
	v_mul_f32_e32 v30, v30, v230
	v_mul_f32_e32 v31, v31, v230
	v_mul_f32_e32 v24, v24, v230
	v_mul_f32_e32 v25, v25, v230
	v_mul_f32_e32 v26, v26, v230
	v_mul_f32_e32 v27, v27, v230
	v_cvt_pk_bf16_f32 v176, v28, v29
	v_cvt_pk_bf16_f32 v177, v30, v31
	v_cvt_pk_bf16_f32 v178, v24, v25
	v_cvt_pk_bf16_f32 v179, v26, v27
	global_store_dwordx4 v[226:227], v[176:179], off
	v_mul_f32_e32 v20, v20, v230
	v_mul_f32_e32 v21, v21, v230
	v_mul_f32_e32 v22, v22, v230
	v_mul_f32_e32 v23, v23, v230
	v_mul_f32_e32 v16, v16, v230
	v_mul_f32_e32 v17, v17, v230
	v_mul_f32_e32 v18, v18, v230
	v_mul_f32_e32 v19, v19, v230
	v_cvt_pk_bf16_f32 v180, v20, v21
	v_cvt_pk_bf16_f32 v181, v22, v23
	v_cvt_pk_bf16_f32 v182, v16, v17
	v_cvt_pk_bf16_f32 v183, v18, v19
	global_store_dwordx4 v[226:227], v[180:183], off offset:256
	v_lshl_add_u64 v[226:227], v[226:227], 0, s[98:99]
	s_waitcnt vmcnt(14)
	v_add_f32_e32 v230, v188, v189
	v_add_f32_e32 v231, v190, v191
	v_add_f32_e32 v232, v194, v195
	v_add_f32_e32 v233, v196, v197
	v_add_f32_e32 v230, v230, v231
	v_add_f32_e32 v232, v232, v233
	v_add_f32_e32 v230, v230, v232
	v_fmamk_f32 v230, v230, 0x3b000000, v241
	v_rsq_f32_e32 v230, v230
	s_nop 0
	v_mul_f32_e32 v12, v12, v230
	v_mul_f32_e32 v13, v13, v230
	v_mul_f32_e32 v14, v14, v230
	v_mul_f32_e32 v15, v15, v230
	v_mul_f32_e32 v8, v8, v230
	v_mul_f32_e32 v9, v9, v230
	v_mul_f32_e32 v10, v10, v230
	v_mul_f32_e32 v11, v11, v230
	v_cvt_pk_bf16_f32 v188, v12, v13
	v_cvt_pk_bf16_f32 v189, v14, v15
	v_cvt_pk_bf16_f32 v190, v8, v9
	v_cvt_pk_bf16_f32 v191, v10, v11
	global_store_dwordx4 v[226:227], v[188:191], off
	v_mul_f32_e32 v4, v4, v230
	v_mul_f32_e32 v5, v5, v230
	v_mul_f32_e32 v6, v6, v230
	v_mul_f32_e32 v7, v7, v230
	v_mul_f32_e32 v0, v0, v230
	v_mul_f32_e32 v1, v1, v230
	v_mul_f32_e32 v2, v2, v230
	v_mul_f32_e32 v3, v3, v230
	v_cvt_pk_bf16_f32 v194, v4, v5
	v_cvt_pk_bf16_f32 v195, v6, v7
	v_cvt_pk_bf16_f32 v196, v0, v1
	v_cvt_pk_bf16_f32 v197, v2, v3
	global_store_dwordx4 v[226:227], v[194:197], off offset:256

; __global__ void __launch_bounds__(NTHR, 2) hybrid_fwd(Params P) {
;     extern __shared__ __attribute__((aligned(16))) unsigned char lds_raw[];
	.amdhsa_kernel _Z10hybrid_fwd6Params
		.amdhsa_group_segment_fixed_size 0
		.amdhsa_private_segment_fixed_size 0
		.amdhsa_kernarg_size 448
		.amdhsa_user_sgpr_count 2
		.amdhsa_user_sgpr_dispatch_ptr 0
		.amdhsa_user_sgpr_queue_ptr 0
		.amdhsa_user_sgpr_kernarg_segment_ptr 1
		.amdhsa_user_sgpr_dispatch_id 0
		.amdhsa_user_sgpr_kernarg_preload_length 0
		.amdhsa_user_sgpr_kernarg_preload_offset 0
		.amdhsa_user_sgpr_private_segment_size 0
		.amdhsa_uses_dynamic_stack 0
		.amdhsa_enable_private_segment 0
		.amdhsa_system_sgpr_workgroup_id_x 1
		.amdhsa_system_sgpr_workgroup_id_y 0
		.amdhsa_system_sgpr_workgroup_id_z 0
		.amdhsa_system_sgpr_workgroup_info 0
		.amdhsa_system_vgpr_workitem_id 2
		.amdhsa_next_free_vgpr 256
		.amdhsa_next_free_sgpr 102
		.amdhsa_accum_offset 256
		.amdhsa_reserve_vcc 1
		.amdhsa_float_round_mode_32 0
		.amdhsa_float_round_mode_16_64 0
		.amdhsa_float_denorm_mode_32 3
		.amdhsa_float_denorm_mode_16_64 3
		.amdhsa_dx10_clamp 1
		.amdhsa_ieee_mode 1
		.amdhsa_fp16_overflow 0
		.amdhsa_tg_split 0
		.amdhsa_exception_fp_ieee_invalid_op 0
		.amdhsa_exception_fp_denorm_src 0
		.amdhsa_exception_fp_ieee_div_zero 0
		.amdhsa_exception_fp_ieee_overflow 0
		.amdhsa_exception_fp_ieee_underflow 0
		.amdhsa_exception_fp_ieee_inexact 0
		.amdhsa_exception_int_div_zero 0
	.end_amdhsa_kernel

; __global__ void __launch_bounds__(NTHR, 2) hybrid_fwd(Params P) {
;     extern __shared__ __attribute__((aligned(16))) unsigned char lds_raw[];
amdhsa.kernels:
  - .agpr_count:     0
    .args:
      - .offset:         0
        .size:           192
        .value_kind:     by_value
      - .offset:         192
        .size:           4
        .value_kind:     hidden_block_count_x
      - .offset:         196
        .size:           4
        .value_kind:     hidden_block_count_y
      - .offset:         200
        .size:           4
        .value_kind:     hidden_block_count_z
      - .offset:         204
        .size:           2
        .value_kind:     hidden_group_size_x
      - .offset:         206
        .size:           2
        .value_kind:     hidden_group_size_y
      - .offset:         208
        .size:           2
        .value_kind:     hidden_group_size_z
      - .offset:         210
        .size:           2
        .value_kind:     hidden_remainder_x
      - .offset:         212
        .size:           2
        .value_kind:     hidden_remainder_y
      - .offset:         214
        .size:           2
        .value_kind:     hidden_remainder_z
      - .offset:         232
        .size:           8
        .value_kind:     hidden_global_offset_x
      - .offset:         240
        .size:           8
        .value_kind:     hidden_global_offset_y
      - .offset:         248
        .size:           8
        .value_kind:     hidden_global_offset_z
      - .offset:         256
        .size:           2
        .value_kind:     hidden_grid_dims
      - .offset:         280
        .size:           8
        .value_kind:     hidden_multigrid_sync_arg
      - .offset:         312
        .size:           4
        .value_kind:     hidden_dynamic_lds_size
    .group_segment_fixed_size: 0
    .kernarg_segment_align: 8
    .kernarg_segment_size: 448
    .language:       OpenCL C
    .language_version:
      - 2
      - 0
    .max_flat_workgroup_size: 512
    .name:           _Z10hybrid_fwd6Params
    .private_segment_fixed_size: 0
    .sgpr_count:     108
    .sgpr_spill_count: 254
    .symbol:         _Z10hybrid_fwd6Params.kd
    .uniform_work_group_size: 1
    .uses_dynamic_stack: false
    .vgpr_count:     256
    .vgpr_spill_count: 0
    .wavefront_size: 64
